# v35 plus nt cache policy on the phase_norm X row loads and the phase_post P row loads
# speedup vs baseline: 1.0172x; 1.0090x over previous
; DI unsigned pk2(float lo, float hi) { f32x2_t v = {lo, hi}; bf16x2_t b = __builtin_convertvector(v, bf16x2_t); return __builtin_bit_cast(unsigned, b); }
; DI float wave_sum(float v) { v += shx(v, 32); v += shx(v, 16); v += shx(v, 8); v += shx(v, 4); v += shx(v, 2); v += shx(v, 1); return v; }
; DI int bid_() { return (int)blockIdx.x; }
; DI void phase_norm(const float* X, const float* nw, bf16_t* H, const float* Wg, int ldw, int col0, float* GATE, lptr lds) {
;     ...
;     for (int rowf = bid_() * 8 + wave; rowf < MTOK; rowf += gridDim.x * 8) {
;         const int row = MTOK - 1 - rowf;
;         f32x4 x[4]; float ss = 0.f;
; #pragma unroll
;         for (int k = 0; k < 4; ++k) { x[k] = *(const f32x4*)(X + (size_t)row * DM + 4 * lane + 256 * k); ss += x[k][0] * x[k][0] + x[k][1] * x[k][1] + x[k][2] * x[k][2] + x[k][3] * x[k][3]; }
;         ss = wave_sum(ss);
;         const float rstd = rsqrtf(ss * (1.f / 1024.f) + EPS);
; #pragma unroll
;         for (int k = 0; k < 4; ++k) { for (int e = 0; e < 4; ++e) x[k][e] = x[k][e] * rstd * wv[k][e];
;             u32x2 w; w.x = pk2(x[k][0], x[k][1]); w.y = pk2(x[k][2], x[k][3]); *(u32x2*)(H + (size_t)row * DM + 4 * lane + 256 * k) = w; }
;         if (Wg) {
;             float g[8]; for (int e = 0; e < 8; ++e) g[e] = 0.f;
; #pragma unroll
;             for (int k = 0; k < 4; ++k)
; #pragma unroll
;                 for (int q = 0; q < 8; ++q) { const f32x4 w4 = lld<f32x4>(lds, 32768 + (q * 1024 + 4 * lane + 256 * k) * 4);
;                     g[q] += x[k][0] * w4[0] + x[k][1] * w4[1] + x[k][2] * w4[2] + x[k][3] * w4[3]; }
.LBB0_94:
	v_sub_u32_e32 v0, 0x7fff, v74
	v_lshlrev_b64 v[8:9], 12, v[0:1]
	v_lshl_add_u64 v[24:25], v[38:39], 0, v[8:9]
	global_load_dwordx4 v[8:11], v[24:25], off nt
	global_load_dwordx4 v[16:19], v[24:25], off offset:1024 nt
	global_load_dwordx4 v[20:23], v[24:25], off offset:2048 nt
	s_nop 0
	global_load_dwordx4 v[24:27], v[24:25], off offset:3072 nt
	v_mov_b32_e32 v28, v194
	s_andn2_b64 vcc, exec, s[56:57]
	v_lshlrev_b32_e32 v28, 2, v28
	v_bitop3_b32 v32, v28, s29, v199 bitop3:0x6c
	s_waitcnt vmcnt(3)
	v_mov_b32_e32 v28, v8
	s_waitcnt vmcnt(2)
	v_mov_b32_e32 v29, v16
	v_mov_b32_e32 v16, v9
	v_mov_b32_e32 v8, v10
	v_mov_b32_e32 v9, v18
	v_mov_b32_e32 v18, v11
	s_waitcnt vmcnt(1)
	v_mov_b32_e32 v10, v20
	s_waitcnt vmcnt(0)
	v_mov_b32_e32 v11, v24
	v_mov_b32_e32 v24, v21
	v_mov_b32_e32 v20, v22
	v_mov_b32_e32 v21, v26
	v_mov_b32_e32 v26, v23
	v_pk_mul_f32 v[22:23], v[16:17], v[16:17]
	v_pk_mul_f32 v[30:31], v[24:25], v[24:25]
	v_pk_fma_f32 v[22:23], v[28:29], v[28:29], v[22:23]
	v_pk_fma_f32 v[30:31], v[10:11], v[10:11], v[30:31]
	v_pk_fma_f32 v[22:23], v[8:9], v[8:9], v[22:23]
	v_pk_fma_f32 v[30:31], v[20:21], v[20:21], v[30:31]
	v_pk_fma_f32 v[22:23], v[18:19], v[18:19], v[22:23]
	v_pk_fma_f32 v[30:31], v[26:27], v[26:27], v[30:31]
	v_add_f32_e32 v22, v22, v23
	v_add_f32_e32 v22, v22, v30
	v_add_f32_e32 v22, v22, v31
	ds_bpermute_b32 v23, v32, v22
	v_mov_b32_e32 v30, v194
	s_waitcnt lgkmcnt(0)
	v_add_f32_e32 v22, v22, v23
	v_lshlrev_b32_e32 v30, 2, v30
	v_bitop3_b32 v30, v30, 64, v199 bitop3:0x6c
	ds_bpermute_b32 v23, v30, v22
	v_mov_b32_e32 v30, v194
	s_waitcnt lgkmcnt(0)
	v_add_f32_e32 v22, v22, v23
	v_lshlrev_b32_e32 v30, 2, v30
	v_bitop3_b32 v30, v30, 32, v199 bitop3:0x6c
	ds_bpermute_b32 v23, v30, v22
	v_mov_b32_e32 v30, v194
	s_waitcnt lgkmcnt(0)
	v_add_f32_e32 v22, v22, v23
	v_lshlrev_b32_e32 v30, 2, v30
	v_bitop3_b32 v30, v30, 16, v199 bitop3:0x6c
	ds_bpermute_b32 v23, v30, v22
	v_mov_b32_e32 v30, v194
	s_waitcnt lgkmcnt(0)
	v_add_f32_e32 v22, v22, v23
	v_lshlrev_b32_e32 v30, 2, v30
	v_bitop3_b32 v30, v30, 8, v199 bitop3:0x6c
	ds_bpermute_b32 v23, v30, v22
	v_mov_b32_e32 v30, v194
	s_waitcnt lgkmcnt(0)
	v_add_f32_e32 v22, v22, v23
	v_lshlrev_b32_e32 v30, 2, v30
	v_bitop3_b32 v30, v30, 4, v199 bitop3:0x6c
	ds_bpermute_b32 v23, v30, v22
	s_waitcnt lgkmcnt(0)
	v_add_f32_e32 v22, v22, v23
	v_fmamk_f32 v22, v22, 0x3a800000, v195
	v_mul_f32_e32 v23, 0x4b800000, v22
	v_cmp_gt_f32_e64 s[0:1], s72, v22
	s_nop 1
	v_cndmask_b32_e64 v22, v22, v23, s[0:1]
	v_rsq_f32_e32 v30, v22
	v_lshlrev_b64 v[22:23], 11, v[0:1]
	v_lshl_add_u64 v[22:23], v[40:41], 0, v[22:23]
	v_mul_f32_e32 v31, 0x45800000, v30
	v_cndmask_b32_e64 v30, v30, v31, s[0:1]
	v_pk_mul_f32 v[16:17], v[16:17], v[30:31] op_sel_hi:[1,0]
	v_pk_mul_f32 v[18:19], v[18:19], v[30:31] op_sel_hi:[1,0]
	v_pk_mul_f32 v[28:29], v[28:29], v[30:31] op_sel_hi:[1,0]
	v_pk_mul_f32 v[8:9], v[8:9], v[30:31] op_sel_hi:[1,0]
	v_pk_mul_f32 v[24:25], v[24:25], v[30:31] op_sel_hi:[1,0]
	v_pk_mul_f32 v[26:27], v[26:27], v[30:31] op_sel_hi:[1,0]
	v_pk_mul_f32 v[10:11], v[10:11], v[30:31] op_sel_hi:[1,0]
	v_pk_mul_f32 v[20:21], v[20:21], v[30:31] op_sel_hi:[1,0]
	v_pk_mul_f32 v[62:63], v[46:47], v[28:29]
	v_pk_mul_f32 v[66:67], v[14:15], v[16:17]
	v_pk_mul_f32 v[60:61], v[12:13], v[8:9]
	v_pk_mul_f32 v[58:59], v[2:3], v[18:19]
	v_pk_mul_f32 v[52:53], v[44:45], v[10:11]
	v_pk_mul_f32 v[54:55], v[6:7], v[24:25]
	v_pk_mul_f32 v[50:51], v[4:5], v[20:21]
	v_pk_mul_f32 v[48:49], v[42:43], v[26:27]
	v_cvt_pk_bf16_f32 v10, v62, v66
	v_cvt_pk_bf16_f32 v11, v60, v58
	v_cvt_pk_bf16_f32 v16, v63, v67
	v_cvt_pk_bf16_f32 v17, v61, v59
	v_cvt_pk_bf16_f32 v18, v52, v54
	v_cvt_pk_bf16_f32 v19, v50, v48
	v_cvt_pk_bf16_f32 v20, v53, v55
	v_cvt_pk_bf16_f32 v21, v51, v49
	global_store_dwordx2 v[22:23], v[10:11], off
	global_store_dwordx2 v[22:23], v[16:17], off offset:512
	global_store_dwordx2 v[22:23], v[18:19], off offset:1024
	global_store_dwordx2 v[22:23], v[20:21], off offset:1536
	s_cbranch_vccnz .LBB0_93
	v_add_u32_e32 v37, 0, v36
	ds_read_b128 v[16:19], v37 offset:57344
	ds_read_b128 v[76:79], v37 offset:58368
	v_mov_b32_e32 v9, v66
	v_mov_b32_e32 v8, v62
	v_mov_b32_e32 v10, v60
	s_waitcnt lgkmcnt(1)
	v_mul_f32_e32 v20, v9, v17
	v_mov_b32_e32 v11, v58
	v_pk_fma_f32 v[8:9], v[8:9], v[16:17], v[20:21] op_sel_hi:[1,1,0]
	v_mul_f32_e32 v22, v58, v19
	v_pk_fma_f32 v[8:9], v[10:11], v[18:19], v[8:9]
	v_mov_b32_e32 v69, v67
	v_pk_add_f32 v[64:65], v[22:23], v[8:9] op_sel_hi:[0,1]
	ds_read_b128 v[28:31], v37 offset:32768
	ds_read_b128 v[24:27], v37 offset:33792
	ds_read_b128 v[32:35], v37 offset:36864
	ds_read_b128 v[20:23], v37 offset:37888
	ds_read_b128 v[16:19], v37 offset:40960
	ds_read_b128 v[8:11], v37 offset:41984
	ds_read_b128 v[80:83], v37 offset:61440
	ds_read_b128 v[84:87], v37 offset:62464
	v_mov_b32_e32 v68, v63
	s_waitcnt lgkmcnt(8)
	v_mul_f32_e32 v70, v69, v77
	v_pk_fma_f32 v[68:69], v[68:69], v[76:77], v[70:71] op_sel_hi:[1,1,0]
	v_mov_b32_e32 v70, v61
	v_mov_b32_e32 v71, v59
	v_pk_fma_f32 v[68:69], v[70:71], v[78:79], v[68:69]
	v_mul_f32_e32 v70, v59, v79
	v_pk_add_f32 v[68:69], v[70:71], v[68:69] op_sel_hi:[0,1]
	s_waitcnt lgkmcnt(0)
	v_mov_b32_e32 v71, v84
	v_mov_b32_e32 v84, v81
	v_mov_b32_e32 v70, v80
	v_pk_mul_f32 v[76:77], v[66:67], v[84:85]
	v_mov_b32_e32 v73, v54
	v_pk_fma_f32 v[70:71], v[62:63], v[70:71], v[76:77]
	ds_read_b128 v[76:79], v37 offset:59392
	v_mov_b32_e32 v80, v82
	v_mov_b32_e32 v81, v86
	v_mov_b32_e32 v72, v52
	v_pk_fma_f32 v[70:71], v[60:61], v[80:81], v[70:71]
	v_mov_b32_e32 v86, v83
	ds_read_b128 v[80:83], v37 offset:60416
	s_waitcnt lgkmcnt(1)
; DI void phase_norm(const float* X, const float* nw, bf16_t* H, const float* Wg, int ldw, int col0, float* GATE, lptr lds) {
;     ...
;             for (int k = 0; k < 4; ++k)
; #pragma unroll
;                 for (int q = 0; q < 8; ++q) { const f32x4 w4 = lld<f32x4>(lds, 32768 + (q * 1024 + 4 * lane + 256 * k) * 4);
;                     g[q] += x[k][0] * w4[0] + x[k][1] * w4[1] + x[k][2] * w4[2] + x[k][3] * w4[3]; }
	v_mul_f32_e32 v84, v73, v77
	v_pk_fma_f32 v[72:73], v[72:73], v[76:77], v[84:85] op_sel_hi:[1,1,0]
	v_mov_b32_e32 v76, v50
	v_mov_b32_e32 v77, v48
	v_pk_fma_f32 v[72:73], v[76:77], v[78:79], v[72:73]
	v_mul_f32_e32 v76, v48, v79
	v_pk_add_f32 v[72:73], v[76:77], v[72:73] op_sel_hi:[0,1]
	v_mov_b32_e32 v77, v32
	v_mov_b32_e32 v32, v29
	v_mov_b32_e32 v76, v28
	v_pk_mul_f32 v[28:29], v[66:67], v[32:33] op_sel_hi:[0,1]
	v_pk_fma_f32 v[28:29], v[62:63], v[76:77], v[28:29] op_sel_hi:[0,1,1]
	v_mov_b32_e32 v32, v30
	v_mov_b32_e32 v33, v34
	v_pk_fma_f32 v[28:29], v[60:61], v[32:33], v[28:29] op_sel_hi:[0,1,1]
	v_mov_b32_e32 v34, v31
	v_pk_fma_f32 v[32:33], v[58:59], v[34:35], v[28:29] op_sel_hi:[0,1,1]
	v_mov_b32_e32 v29, v20
	v_mov_b32_e32 v20, v25
	v_mov_b32_e32 v28, v24
	v_pk_mul_f32 v[20:21], v[66:67], v[20:21] op_sel:[1,0]
	v_pk_fma_f32 v[70:71], v[58:59], v[86:87], v[70:71]
	ds_read_b128 v[76:79], v37 offset:34816
	ds_read_b128 v[84:87], v37 offset:35840
	v_pk_fma_f32 v[20:21], v[62:63], v[28:29], v[20:21] op_sel:[1,0,0]
	v_mov_b32_e32 v34, v26
	v_mov_b32_e32 v35, v22
	v_mov_b32_e32 v22, v27
	ds_read_b128 v[24:27], v37 offset:38912
	ds_read_b128 v[28:31], v37 offset:39936
	v_pk_fma_f32 v[20:21], v[60:61], v[34:35], v[20:21] op_sel:[1,0,0]
	v_pk_add_f32 v[32:33], v[32:33], 0 op_sel_hi:[1,0]
	v_pk_fma_f32 v[20:21], v[58:59], v[22:23], v[20:21] op_sel:[1,0,0]
	v_mov_b32_e32 v57, v55
	v_pk_add_f32 v[88:89], v[32:33], v[20:21]
	s_waitcnt lgkmcnt(1)
	v_mov_b32_e32 v21, v24
	v_mov_b32_e32 v24, v77
	v_mov_b32_e32 v20, v76
	v_pk_mul_f32 v[22:23], v[54:55], v[24:25] op_sel_hi:[0,1]
	v_pk_fma_f32 v[24:25], v[52:53], v[20:21], v[22:23] op_sel_hi:[0,1,1]
	ds_read_b128 v[20:23], v37 offset:45056
	ds_read_b128 v[32:35], v37 offset:46080
	v_mov_b32_e32 v76, v78
	v_mov_b32_e32 v77, v26
	v_mov_b32_e32 v26, v79
	v_pk_fma_f32 v[24:25], v[50:51], v[76:77], v[24:25] op_sel_hi:[0,1,1]
	v_pk_fma_f32 v[24:25], v[48:49], v[26:27], v[24:25] op_sel_hi:[0,1,1]
	v_pk_add_f32 v[88:89], v[88:89], v[24:25]
	s_waitcnt lgkmcnt(2)
	v_mov_b32_e32 v25, v28
	v_mov_b32_e32 v28, v85
	s_waitcnt lgkmcnt(1)
	v_mov_b32_e32 v77, v20
	v_mov_b32_e32 v20, v17
	v_mov_b32_e32 v24, v84
	v_pk_mul_f32 v[26:27], v[54:55], v[28:29] op_sel:[1,0]
	v_mov_b32_e32 v76, v16
	v_pk_mul_f32 v[16:17], v[66:67], v[20:21] op_sel_hi:[0,1]
	v_pk_fma_f32 v[24:25], v[52:53], v[24:25], v[26:27] op_sel:[1,0,0]
	v_mov_b32_e32 v26, v86
	v_mov_b32_e32 v27, v30
	v_pk_fma_f32 v[16:17], v[62:63], v[76:77], v[16:17] op_sel_hi:[0,1,1]
	v_mov_b32_e32 v20, v18
	v_mov_b32_e32 v21, v22
	v_pk_fma_f32 v[24:25], v[50:51], v[26:27], v[24:25] op_sel:[1,0,0]
	v_mov_b32_e32 v30, v87
	v_pk_fma_f32 v[20:21], v[60:61], v[20:21], v[16:17] op_sel_hi:[0,1,1]
	v_mov_b32_e32 v22, v19
	v_pk_fma_f32 v[84:85], v[48:49], v[30:31], v[24:25] op_sel:[1,0,0]
	ds_read_b128 v[24:27], v37 offset:43008
	ds_read_b128 v[28:31], v37 offset:44032
	ds_read_b128 v[16:19], v37 offset:47104
	ds_read_b128 v[76:79], v37 offset:48128
	v_pk_fma_f32 v[86:87], v[58:59], v[22:23], v[20:21] op_sel_hi:[0,1,1]
	s_waitcnt lgkmcnt(4)
	v_mov_b32_e32 v21, v32
	v_mov_b32_e32 v32, v9
	v_mov_b32_e32 v20, v8
	v_pk_mul_f32 v[8:9], v[66:67], v[32:33] op_sel:[1,0]
	v_mov_b32_e32 v56, v53
	v_pk_fma_f32 v[8:9], v[62:63], v[20:21], v[8:9] op_sel:[1,0,0]
	v_mov_b32_e32 v20, v10
	v_mov_b32_e32 v21, v34
	v_pk_fma_f32 v[8:9], v[60:61], v[20:21], v[8:9] op_sel:[1,0,0]
	v_mov_b32_e32 v34, v11
	v_pk_fma_f32 v[10:11], v[58:59], v[34:35], v[8:9] op_sel:[1,0,0]
	s_waitcnt lgkmcnt(1)
	v_mov_b32_e32 v9, v16
	v_mov_b32_e32 v16, v25
	v_mov_b32_e32 v8, v24
	v_pk_mul_f32 v[16:17], v[54:55], v[16:17] op_sel_hi:[0,1]
	v_pk_fma_f32 v[8:9], v[52:53], v[8:9], v[16:17] op_sel_hi:[0,1,1]
	v_mov_b32_e32 v16, v26
	v_mov_b32_e32 v17, v18
	v_pk_fma_f32 v[8:9], v[50:51], v[16:17], v[8:9] op_sel_hi:[0,1,1]
	v_mov_b32_e32 v18, v27
	ds_read_b128 v[20:23], v37 offset:49152
	ds_read_b128 v[32:35], v37 offset:50176
	v_pk_fma_f32 v[90:91], v[48:49], v[18:19], v[8:9] op_sel_hi:[0,1,1]
	ds_read_b128 v[16:19], v37 offset:53248
	ds_read_b128 v[24:27], v37 offset:54272
	v_pk_add_f32 v[8:9], v[88:89], v[84:85]
	v_pk_add_f32 v[84:85], v[86:87], 0 op_sel_hi:[1,0]
	v_mov_b32_e32 v65, v70
	v_pk_add_f32 v[10:11], v[84:85], v[10:11]
	s_waitcnt lgkmcnt(4)
	v_mov_b32_e32 v85, v76
	v_mov_b32_e32 v76, v29
	v_mov_b32_e32 v84, v28
	v_pk_mul_f32 v[28:29], v[54:55], v[76:77] op_sel:[1,0]
	v_mov_b32_e32 v76, v30
	v_pk_fma_f32 v[28:29], v[52:53], v[84:85], v[28:29] op_sel:[1,0,0]
	s_waitcnt lgkmcnt(1)
	v_mov_b32_e32 v85, v16
	v_mov_b32_e32 v16, v21
	v_mov_b32_e32 v84, v20
	v_pk_mul_f32 v[16:17], v[66:67], v[16:17] op_sel_hi:[0,1]
	v_mov_b32_e32 v77, v78
	v_pk_fma_f32 v[16:17], v[62:63], v[84:85], v[16:17] op_sel_hi:[0,1,1]
	v_mov_b32_e32 v20, v22
	v_mov_b32_e32 v21, v18
	v_pk_fma_f32 v[28:29], v[50:51], v[76:77], v[28:29] op_sel:[1,0,0]
	v_mov_b32_e32 v78, v31
	v_pk_fma_f32 v[16:17], v[60:61], v[20:21], v[16:17] op_sel_hi:[0,1,1]
	v_mov_b32_e32 v18, v23
	v_pk_add_f32 v[10:11], v[10:11], v[90:91]
	v_pk_fma_f32 v[28:29], v[48:49], v[78:79], v[28:29] op_sel:[1,0,0]
	v_pk_fma_f32 v[16:17], v[58:59], v[18:19], v[16:17] op_sel_hi:[0,1,1]
	s_waitcnt lgkmcnt(0)
	v_mov_b32_e32 v19, v24
	v_mov_b32_e32 v24, v33
	v_pk_add_f32 v[10:11], v[10:11], v[28:29]
	ds_read_b128 v[28:31], v37 offset:51200
	ds_read_b128 v[76:79], v37 offset:52224
	ds_read_b128 v[20:23], v37 offset:55296
	ds_read_b128 v[84:87], v37 offset:56320
	v_mov_b32_e32 v18, v32
	v_pk_mul_f32 v[24:25], v[66:67], v[24:25] op_sel:[1,0]
	v_pk_add_f32 v[16:17], v[16:17], 0 op_sel_hi:[1,0]
	v_pk_fma_f32 v[18:19], v[62:63], v[18:19], v[24:25] op_sel:[1,0,0]
	v_mov_b32_e32 v24, v34
	v_mov_b32_e32 v25, v26
	v_pk_fma_f32 v[18:19], v[60:61], v[24:25], v[18:19] op_sel:[1,0,0]
	v_mov_b32_e32 v26, v35
	v_pk_fma_f32 v[18:19], v[58:59], v[26:27], v[18:19] op_sel:[1,0,0]
	v_mov_b32_e32 v69, v71
	v_pk_add_f32 v[16:17], v[16:17], v[18:19]
	s_waitcnt lgkmcnt(1)
; DI float wave_sum(float v) { v += shx(v, 32); v += shx(v, 16); v += shx(v, 8); v += shx(v, 4); v += shx(v, 2); v += shx(v, 1); return v; }
; DI void phase_norm(const float* X, const float* nw, bf16_t* H, const float* Wg, int ldw, int col0, float* GATE, lptr lds) {
;     ...
;                 for (int q = 0; q < 8; ++q) { const f32x4 w4 = lld<f32x4>(lds, 32768 + (q * 1024 + 4 * lane + 256 * k) * 4);
;                     g[q] += x[k][0] * w4[0] + x[k][1] * w4[1] + x[k][2] * w4[2] + x[k][3] * w4[3]; }
;             for (int e = 0; e < 8; ++e) g[e] = wave_sum(g[e]);
;             if (lane == 0) { *(f32x4*)(GATE + (size_t)row * 8) = (f32x4){g[0], g[1], g[2], g[3]}; *(f32x4*)(GATE + (size_t)row * 8 + 4) = (f32x4){g[4], g[5], g[6], g[7]}; }
	v_mov_b32_e32 v19, v20
	v_mov_b32_e32 v20, v29
	v_mov_b32_e32 v18, v28
	v_pk_mul_f32 v[20:21], v[54:55], v[20:21] op_sel_hi:[0,1]
	v_pk_fma_f32 v[18:19], v[52:53], v[18:19], v[20:21] op_sel_hi:[0,1,1]
	v_mov_b32_e32 v20, v30
	v_mov_b32_e32 v21, v22
	v_pk_fma_f32 v[18:19], v[50:51], v[20:21], v[18:19] op_sel_hi:[0,1,1]
	v_mov_b32_e32 v22, v31
	v_pk_fma_f32 v[18:19], v[48:49], v[22:23], v[18:19] op_sel_hi:[0,1,1]
	v_pk_add_f32 v[16:17], v[16:17], v[18:19]
	s_waitcnt lgkmcnt(0)
	v_mov_b32_e32 v19, v84
	v_mov_b32_e32 v84, v77
	v_mov_b32_e32 v18, v76
	v_pk_mul_f32 v[20:21], v[54:55], v[84:85] op_sel:[1,0]
	v_mov_b32_e32 v28, v51
	v_pk_fma_f32 v[18:19], v[52:53], v[18:19], v[20:21] op_sel:[1,0,0]
	v_mov_b32_e32 v20, v78
	v_mov_b32_e32 v21, v86
	v_pk_fma_f32 v[18:19], v[50:51], v[20:21], v[18:19] op_sel:[1,0,0]
	v_mov_b32_e32 v86, v79
	v_pk_fma_f32 v[18:19], v[48:49], v[86:87], v[18:19] op_sel:[1,0,0]
	v_mov_b32_e32 v29, v49
	v_pk_add_f32 v[16:17], v[16:17], v[18:19]
	v_mul_f32_e32 v18, v57, v81
	v_pk_fma_f32 v[26:27], v[56:57], v[80:81], v[18:19] op_sel_hi:[1,1,0]
	ds_read_b128 v[18:21], v37 offset:63488
	ds_read_b128 v[22:25], v37 offset:64512
	v_pk_fma_f32 v[26:27], v[28:29], v[82:83], v[26:27]
	v_mul_f32_e32 v28, v49, v83
	v_pk_add_f32 v[26:27], v[28:29], v[26:27] op_sel_hi:[0,1]
	s_waitcnt lgkmcnt(1)
	v_mov_b32_e32 v28, v18
	s_waitcnt lgkmcnt(0)
	v_mov_b32_e32 v29, v22
	v_mov_b32_e32 v22, v19
	v_pk_mul_f32 v[18:19], v[54:55], v[22:23]
	v_mov_b32_e32 v22, v20
	v_pk_fma_f32 v[18:19], v[52:53], v[28:29], v[18:19]
	v_mov_b32_e32 v23, v24
	v_pk_fma_f32 v[18:19], v[50:51], v[22:23], v[18:19]
	v_mov_b32_e32 v24, v21
	v_pk_fma_f32 v[18:19], v[48:49], v[24:25], v[18:19]
	v_pk_add_f32 v[20:21], v[64:65], 0 op_sel_hi:[1,0]
	v_mov_b32_e32 v73, v18
	v_pk_add_f32 v[20:21], v[20:21], v[68:69]
	v_mov_b32_e32 v27, v19
	v_pk_add_f32 v[20:21], v[20:21], v[72:73]
	s_mov_b64 s[2:3], 0
	v_pk_add_f32 v[18:19], v[20:21], v[26:27]
	v_lshlrev_b32_e32 v106, 2, v194
	v_bitop3_b32 v100, v106, s29, v199 bitop3:0x6c
	v_bitop3_b32 v101, v106, 64, v199 bitop3:0x6c
	v_bitop3_b32 v102, v106, 32, v199 bitop3:0x6c
	v_bitop3_b32 v103, v106, 16, v199 bitop3:0x6c
	v_bitop3_b32 v104, v106, 8, v199 bitop3:0x6c
	v_bitop3_b32 v105, v106, 4, v199 bitop3:0x6c
	ds_bpermute_b32 v92, v100, v8
	ds_bpermute_b32 v93, v100, v9
	ds_bpermute_b32 v94, v100, v10
	ds_bpermute_b32 v95, v100, v11
	ds_bpermute_b32 v96, v100, v16
	ds_bpermute_b32 v97, v100, v17
	ds_bpermute_b32 v98, v100, v18
	ds_bpermute_b32 v99, v100, v19
	s_waitcnt lgkmcnt(7)
	v_add_f32_e32 v8, v8, v92
	s_waitcnt lgkmcnt(6)
	v_add_f32_e32 v9, v9, v93
	s_waitcnt lgkmcnt(5)
	v_add_f32_e32 v10, v10, v94
	s_waitcnt lgkmcnt(4)
	v_add_f32_e32 v11, v11, v95
	s_waitcnt lgkmcnt(3)
	v_add_f32_e32 v16, v16, v96
	s_waitcnt lgkmcnt(2)
	v_add_f32_e32 v17, v17, v97
	s_waitcnt lgkmcnt(1)
	v_add_f32_e32 v18, v18, v98
	s_waitcnt lgkmcnt(0)
	v_add_f32_e32 v19, v19, v99
	ds_bpermute_b32 v92, v101, v8
	ds_bpermute_b32 v93, v101, v9
	ds_bpermute_b32 v94, v101, v10
	ds_bpermute_b32 v95, v101, v11
	ds_bpermute_b32 v96, v101, v16
	ds_bpermute_b32 v97, v101, v17
	ds_bpermute_b32 v98, v101, v18
	ds_bpermute_b32 v99, v101, v19
	s_waitcnt lgkmcnt(7)
	v_add_f32_e32 v8, v8, v92
	s_waitcnt lgkmcnt(6)
	v_add_f32_e32 v9, v9, v93
	s_waitcnt lgkmcnt(5)
	v_add_f32_e32 v10, v10, v94
	s_waitcnt lgkmcnt(4)
	v_add_f32_e32 v11, v11, v95
	s_waitcnt lgkmcnt(3)
	v_add_f32_e32 v16, v16, v96
	s_waitcnt lgkmcnt(2)
	v_add_f32_e32 v17, v17, v97
	s_waitcnt lgkmcnt(1)
	v_add_f32_e32 v18, v18, v98
	s_waitcnt lgkmcnt(0)
	v_add_f32_e32 v19, v19, v99
	ds_bpermute_b32 v92, v102, v8
	ds_bpermute_b32 v93, v102, v9
	ds_bpermute_b32 v94, v102, v10
	ds_bpermute_b32 v95, v102, v11
	ds_bpermute_b32 v96, v102, v16
	ds_bpermute_b32 v97, v102, v17
	ds_bpermute_b32 v98, v102, v18
	ds_bpermute_b32 v99, v102, v19
	s_waitcnt lgkmcnt(7)
	v_add_f32_e32 v8, v8, v92
	s_waitcnt lgkmcnt(6)
	v_add_f32_e32 v9, v9, v93
	s_waitcnt lgkmcnt(5)
	v_add_f32_e32 v10, v10, v94
	s_waitcnt lgkmcnt(4)
	v_add_f32_e32 v11, v11, v95
	s_waitcnt lgkmcnt(3)
	v_add_f32_e32 v16, v16, v96
	s_waitcnt lgkmcnt(2)
	v_add_f32_e32 v17, v17, v97
	s_waitcnt lgkmcnt(1)
	v_add_f32_e32 v18, v18, v98
	s_waitcnt lgkmcnt(0)
	v_add_f32_e32 v19, v19, v99
	ds_bpermute_b32 v92, v103, v8
	ds_bpermute_b32 v93, v103, v9
	ds_bpermute_b32 v94, v103, v10
	ds_bpermute_b32 v95, v103, v11
	ds_bpermute_b32 v96, v103, v16
	ds_bpermute_b32 v97, v103, v17
	ds_bpermute_b32 v98, v103, v18
	ds_bpermute_b32 v99, v103, v19
	s_waitcnt lgkmcnt(7)
	v_add_f32_e32 v8, v8, v92
	s_waitcnt lgkmcnt(6)
	v_add_f32_e32 v9, v9, v93
	s_waitcnt lgkmcnt(5)
	v_add_f32_e32 v10, v10, v94
	s_waitcnt lgkmcnt(4)
	v_add_f32_e32 v11, v11, v95
	s_waitcnt lgkmcnt(3)
	v_add_f32_e32 v16, v16, v96
	s_waitcnt lgkmcnt(2)
	v_add_f32_e32 v17, v17, v97
	s_waitcnt lgkmcnt(1)
	v_add_f32_e32 v18, v18, v98
	s_waitcnt lgkmcnt(0)
	v_add_f32_e32 v19, v19, v99
	ds_bpermute_b32 v92, v104, v8
	ds_bpermute_b32 v93, v104, v9
	ds_bpermute_b32 v94, v104, v10
	ds_bpermute_b32 v95, v104, v11
	ds_bpermute_b32 v96, v104, v16
	ds_bpermute_b32 v97, v104, v17
	ds_bpermute_b32 v98, v104, v18
	ds_bpermute_b32 v99, v104, v19
	s_waitcnt lgkmcnt(7)
	v_add_f32_e32 v8, v8, v92
	s_waitcnt lgkmcnt(6)
	v_add_f32_e32 v9, v9, v93
	s_waitcnt lgkmcnt(5)
	v_add_f32_e32 v10, v10, v94
	s_waitcnt lgkmcnt(4)
	v_add_f32_e32 v11, v11, v95
	s_waitcnt lgkmcnt(3)
	v_add_f32_e32 v16, v16, v96
	s_waitcnt lgkmcnt(2)
	v_add_f32_e32 v17, v17, v97
	s_waitcnt lgkmcnt(1)
	v_add_f32_e32 v18, v18, v98
	s_waitcnt lgkmcnt(0)
	v_add_f32_e32 v19, v19, v99
	ds_bpermute_b32 v92, v105, v8
	ds_bpermute_b32 v93, v105, v9
	ds_bpermute_b32 v94, v105, v10
	ds_bpermute_b32 v95, v105, v11
	ds_bpermute_b32 v96, v105, v16
	ds_bpermute_b32 v97, v105, v17
	ds_bpermute_b32 v98, v105, v18
	ds_bpermute_b32 v99, v105, v19
	s_waitcnt lgkmcnt(7)
	v_add_f32_e32 v8, v8, v92
	s_waitcnt lgkmcnt(6)
	v_add_f32_e32 v9, v9, v93
	s_waitcnt lgkmcnt(5)
	v_add_f32_e32 v10, v10, v94
	s_waitcnt lgkmcnt(4)
	v_add_f32_e32 v11, v11, v95
	s_waitcnt lgkmcnt(3)
	v_add_f32_e32 v16, v16, v96
	s_waitcnt lgkmcnt(2)
	v_add_f32_e32 v17, v17, v97
	s_waitcnt lgkmcnt(1)
	v_add_f32_e32 v18, v18, v98
	s_waitcnt lgkmcnt(0)
	v_add_f32_e32 v19, v19, v99
	s_and_saveexec_b64 s[0:1], s[38:39]
	s_cbranch_execz .LBB0_92
	v_readlane_b32 s2, v250, 41
	v_lshlrev_b64 v[20:21], 5, v[0:1]
	v_readlane_b32 s3, v250, 42
	s_nop 1
	v_lshl_add_u64 v[20:21], s[2:3], 0, v[20:21]
	global_store_dwordx4 v[20:21], v[8:11], off
	global_store_dwordx4 v[20:21], v[16:19], off offset:16
	s_branch .LBB0_92

; DI int tid_() { int t = threadIdx.x; asm volatile("" : "+v"(t)); return t; }
; DI float wave_sum(float v) { v += shx(v, 32); v += shx(v, 16); v += shx(v, 8); v += shx(v, 4); v += shx(v, 2); v += shx(v, 1); return v; }
; DI void phase_post(const Params& p, int L) {
;     ...
;     const int tid = tid_(), wave = tid >> 6, lane = tid & 63;
;     const float lambda_init = 0.8f - 0.6f * __expf(-0.3f * (float)L);
;     const float s1 = wave_sum(p.in[11][j * 64 + lane] * p.in[12][j * 64 + lane]), s2 = wave_sum(p.in[13][j * 64 + lane] * p.in[14][j * 64 + lane]);
;     const float lam = expf(s1) - expf(s2) + lambda_init;
.LBB0_610:
	s_or_b64 exec, exec, s[0:1]
	v_mov_b32_e32 v3, v194
	s_waitcnt lgkmcnt(0)
	s_barrier
	v_readlane_b32 s36, v250, 5
	v_and_b32_e32 v2, 63, v3
	v_lshl_or_b32 v0, s56, 5, v2
	v_lshlrev_b64 v[8:9], 2, v[0:1]
	v_readlane_b32 s42, v250, 11
	v_readlane_b32 s43, v250, 12
	v_readlane_b32 s44, v250, 13
	v_readlane_b32 s45, v250, 14
	v_lshl_add_u64 v[4:5], s[42:43], 0, v[8:9]
	global_load_dword v0, v[4:5], off
	v_lshl_add_u64 v[4:5], s[44:45], 0, v[8:9]
	global_load_dword v4, v[4:5], off
	v_mov_b32_e32 v7, v194
	v_readlane_b32 s46, v250, 15
	v_lshlrev_b32_e32 v7, 2, v7
	v_bitop3_b32 v7, v7, s29, v199 bitop3:0x6c
	v_readlane_b32 s47, v250, 16
	v_readlane_b32 s48, v250, 17
	v_readlane_b32 s49, v250, 18
	v_lshl_add_u64 v[10:11], s[46:47], 0, v[8:9]
	v_ashrrev_i32_e32 v6, 6, v3
	v_lshl_add_u64 v[8:9], s[48:49], 0, v[8:9]
	v_readlane_b32 s0, v250, 55
	v_readlane_b32 s37, v250, 6
	v_readlane_b32 s38, v250, 7
	v_readlane_b32 s39, v250, 8
	v_readlane_b32 s40, v250, 9
	v_readlane_b32 s41, v250, 10
	v_readlane_b32 s50, v250, 19
	v_readlane_b32 s51, v250, 20
	s_waitcnt vmcnt(0)
	v_mul_f32_e32 v5, v0, v4
	ds_bpermute_b32 v5, v7, v5
	s_waitcnt lgkmcnt(0)
	v_fmac_f32_e32 v5, v0, v4
	v_mov_b32_e32 v0, v194
	v_mov_b32_e32 v4, v194
	v_lshlrev_b32_e32 v0, 2, v0
	v_bitop3_b32 v0, v0, 64, v199 bitop3:0x6c
	ds_bpermute_b32 v0, v0, v5
	s_waitcnt lgkmcnt(0)
	v_add_f32_e32 v0, v5, v0
	v_lshlrev_b32_e32 v4, 2, v4
	v_bitop3_b32 v4, v4, 32, v199 bitop3:0x6c
	ds_bpermute_b32 v4, v4, v0
	s_waitcnt lgkmcnt(0)
	v_add_f32_e32 v0, v0, v4
	v_mov_b32_e32 v4, v194
	s_nop 0
	v_lshlrev_b32_e32 v4, 2, v4
	v_bitop3_b32 v4, v4, 16, v199 bitop3:0x6c
	ds_bpermute_b32 v4, v4, v0
	s_waitcnt lgkmcnt(0)
	v_add_f32_e32 v0, v0, v4
	v_mov_b32_e32 v4, v194
	s_nop 0
	v_lshlrev_b32_e32 v4, 2, v4
	v_bitop3_b32 v4, v4, 8, v199 bitop3:0x6c
	ds_bpermute_b32 v4, v4, v0
	s_waitcnt lgkmcnt(0)
	v_add_f32_e32 v4, v0, v4
	v_mov_b32_e32 v0, v194
	global_load_dword v7, v[8:9], off
	v_lshlrev_b32_e32 v0, 2, v0
	v_bitop3_b32 v0, v0, 4, v199 bitop3:0x6c
	ds_bpermute_b32 v5, v0, v4
	global_load_dword v0, v[10:11], off
	v_mov_b32_e32 v9, v194
	v_add_u32_e32 v10, s0, v6
	v_lshlrev_b32_e32 v9, 2, v9
	v_bitop3_b32 v9, v9, s29, v199 bitop3:0x6c
	s_mov_b32 s0, 0x8000
	v_cmp_gt_i32_e32 vcc, s0, v10
	s_waitcnt vmcnt(0)
	v_mul_f32_e32 v8, v0, v7
	ds_bpermute_b32 v8, v9, v8
	s_waitcnt lgkmcnt(0)
	v_fmac_f32_e32 v8, v0, v7
	v_mov_b32_e32 v0, v194
	v_mov_b32_e32 v7, v194
	v_lshlrev_b32_e32 v0, 2, v0
	v_bitop3_b32 v0, v0, 64, v199 bitop3:0x6c
	ds_bpermute_b32 v0, v0, v8
	s_waitcnt lgkmcnt(0)
	v_add_f32_e32 v0, v8, v0
	v_lshlrev_b32_e32 v7, 2, v7
	v_bitop3_b32 v7, v7, 32, v199 bitop3:0x6c
	ds_bpermute_b32 v7, v7, v0
	s_waitcnt lgkmcnt(0)
	v_add_f32_e32 v0, v0, v7
	v_mov_b32_e32 v7, v194
	s_nop 0
	v_lshlrev_b32_e32 v7, 2, v7
	v_bitop3_b32 v7, v7, 16, v199 bitop3:0x6c
	ds_bpermute_b32 v7, v7, v0
	s_waitcnt lgkmcnt(0)
	v_add_f32_e32 v0, v0, v7
	v_mov_b32_e32 v7, v194
	s_nop 0
	v_lshlrev_b32_e32 v7, 2, v7
	v_bitop3_b32 v7, v7, 8, v199 bitop3:0x6c
	ds_bpermute_b32 v7, v7, v0
	s_waitcnt lgkmcnt(0)
	v_add_f32_e32 v7, v0, v7
	v_mov_b32_e32 v0, v194
	s_nop 0
	v_lshlrev_b32_e32 v0, 2, v0
	v_bitop3_b32 v0, v0, 4, v199 bitop3:0x6c
	ds_bpermute_b32 v8, v0, v7
	s_and_saveexec_b64 s[0:1], vcc
	s_cbranch_execz .LBB0_619
; DI float bflo(unsigned w) { return __uint_as_float(w << 16); }
; DI float bfhi(unsigned w) { return __uint_as_float(w & 0xffff0000u); }
; DI float wave_sum(float v) { v += shx(v, 32); v += shx(v, 16); v += shx(v, 8); v += shx(v, 4); v += shx(v, 2); v += shx(v, 1); return v; }
; DI int bid_() { return (int)blockIdx.x; }
; DI void phase_post(const Params& p, int L) {
;     ...
;     const float lambda_init = 0.8f - 0.6f * __expf(-0.3f * (float)L);
;     const float s1 = wave_sum(p.in[11][j * 64 + lane] * p.in[12][j * 64 + lane]), s2 = wave_sum(p.in[13][j * 64 + lane] * p.in[14][j * 64 + lane]);
;     const float lam = expf(s1) - expf(s2) + lambda_init;
;     const bool isa = lane < 32; const int d0 = (lane & 7) * 16;
;     float nw[16];
;     { const float* src = isa ? (p.in[10] + j * 128 + d0) : (p.in[15] + j * 128 + d0); for (int e = 0; e < 16; ++e) nw[e] = src[e] * (isa ? 1.f : (1.f - lambda_init)); }
;     for (int row = bid_() * 8 + wave; row < MTOK; row += gridDim.x * 8) {
;         const bf16_t* pr = P + (size_t)row * PE;
;         float o[16];
;         if (isa) { const u32x4 a = *(const u32x4*)(pr + 1024 + 16 * lane), bq = *(const u32x4*)(pr + 1024 + 16 * lane + 8);
;             const unsigned uw[8] = {a.x, a.y, a.z, a.w, bq.x, bq.y, bq.z, bq.w};
;             for (int q = 0; q < 8; ++q) { o[2 * q] = bflo(uw[q]); o[2 * q + 1] = bfhi(uw[q]); } }
;         else { const int l2 = lane - 32;
;             const u32x4 a = *(const u32x4*)(pr + 16 * l2), bq = *(const u32x4*)(pr + 16 * l2 + 8), c = *(const u32x4*)(pr + 512 + 16 * l2), d = *(const u32x4*)(pr + 512 + 16 * l2 + 8);
;             const unsigned u1[8] = {a.x, a.y, a.z, a.w, bq.x, bq.y, bq.z, bq.w}, u2[8] = {c.x, c.y, c.z, c.w, d.x, d.y, d.z, d.w};
;             for (int q = 0; q < 8; ++q) { o[2 * q] = bflo(u1[q]) - lam * bflo(u2[q]); o[2 * q + 1] = bfhi(u1[q]) - lam * bfhi(u2[q]); } }
	v_cvt_f32_u32_e32 v0, s56
	s_lshl_b32 s82, s56, 6
	s_mov_b32 s2, s56
	v_readlane_b32 s44, v250, 5
	v_mul_f32_e32 v0, 0xbe99999a, v0
	v_mul_f32_e32 v0, 0x3fb8aa3b, v0
	v_exp_f32_e32 v0, v0
	v_readlane_b32 s49, v250, 10
	v_readlane_b32 s59, v250, 20
	v_cmp_gt_u32_e64 s[40:41], 32, v2
	v_fmamk_f32 v6, v0, 0xbf19999a, v198
	v_readlane_b32 s48, v250, 9
	v_readlane_b32 s58, v250, 19
	v_mov_b32_e32 v0, s59
	v_mov_b32_e32 v11, s49
	v_cndmask_b32_e64 v13, v0, v11, s[40:41]
	v_mov_b32_e32 v0, s58
	v_mov_b32_e32 v11, s48
	v_cndmask_b32_e64 v12, v0, v11, s[40:41]
	v_lshlrev_b32_e32 v0, 6, v3
	v_lshl_add_u64 v[12:13], s[82:83], 2, v[12:13]
	v_and_b32_e32 v0, 0x1c0, v0
	v_lshl_add_u64 v[12:13], v[12:13], 0, v[0:1]
	global_load_dwordx4 v[24:27], v[12:13], off offset:48
	global_load_dwordx4 v[20:23], v[12:13], off offset:32
	global_load_dwordx4 v[16:19], v[12:13], off offset:16
	s_nop 0
	global_load_dwordx4 v[12:15], v[12:13], off
	v_sub_f32_e32 v9, 1.0, v6
	v_cndmask_b32_e64 v0, v9, 1.0, s[40:41]
	v_readlane_b32 s56, v250, 17
	s_mov_b32 s56, s2
	s_mov_b32 s2, 0x3fb8aa3b
	s_mov_b32 s3, 0xc2ce8ed0
	s_mov_b32 s10, 0x42b17218
	v_lshlrev_b32_e32 v30, 4, v2
	v_cmp_lt_u32_e64 s[38:39], 31, v2
	v_add_u32_e32 v32, 0xfffffe00, v30
	v_mov_b32_e32 v33, v1
	s_mov_b64 s[42:43], 0
	v_readlane_b32 s45, v250, 6
	v_readlane_b32 s46, v250, 7
	v_readlane_b32 s47, v250, 8
	v_readlane_b32 s50, v250, 11
	v_readlane_b32 s51, v250, 12
	v_readlane_b32 s52, v250, 13
	v_readlane_b32 s53, v250, 14
	v_readlane_b32 s54, v250, 15
	v_readlane_b32 s55, v250, 16
	v_readlane_b32 s57, v250, 18
	s_waitcnt vmcnt(3)
	v_pk_mul_f32 v[24:25], v[0:1], v[24:25] op_sel_hi:[0,1]
	s_waitcnt vmcnt(2)
	v_pk_mul_f32 v[20:21], v[0:1], v[20:21] op_sel_hi:[0,1]
	s_waitcnt vmcnt(1)
	v_pk_mul_f32 v[16:17], v[0:1], v[16:17] op_sel_hi:[0,1]
	s_waitcnt vmcnt(0)
	v_pk_mul_f32 v[12:13], v[0:1], v[12:13] op_sel_hi:[0,1]
	v_pk_mul_f32 v[14:15], v[0:1], v[14:15] op_sel_hi:[0,1]
	v_pk_mul_f32 v[18:19], v[0:1], v[18:19] op_sel_hi:[0,1]
	v_pk_mul_f32 v[22:23], v[0:1], v[22:23] op_sel_hi:[0,1]
	v_pk_mul_f32 v[26:27], v[0:1], v[26:27] op_sel_hi:[0,1]
	v_add_f32_e32 v0, v4, v5
	v_mul_f32_e32 v3, 0x3fb8aa3b, v0
	v_fma_f32 v4, v0, s2, -v3
	v_rndne_f32_e32 v5, v3
	v_fmac_f32_e32 v4, 0x32a5705f, v0
	v_sub_f32_e32 v3, v3, v5
	v_add_f32_e32 v3, v3, v4
	v_exp_f32_e32 v3, v3
	v_cvt_i32_f32_e32 v4, v5
	v_cmp_ngt_f32_e32 vcc, s3, v0
	v_ldexp_f32 v3, v3, v4
	s_nop 0
	v_cndmask_b32_e32 v3, 0, v3, vcc
	v_cmp_nlt_f32_e32 vcc, s10, v0
	s_nop 1
	v_cndmask_b32_e32 v0, v200, v3, vcc
	s_waitcnt lgkmcnt(0)
	v_add_f32_e32 v3, v7, v8
	v_mul_f32_e32 v4, 0x3fb8aa3b, v3
	v_fma_f32 v5, v3, s2, -v4
	v_rndne_f32_e32 v7, v4
	v_fmac_f32_e32 v5, 0x32a5705f, v3
	v_sub_f32_e32 v4, v4, v7
	v_add_f32_e32 v4, v4, v5
	v_exp_f32_e32 v4, v4
	v_cvt_i32_f32_e32 v5, v7
	v_cmp_ngt_f32_e32 vcc, s3, v3
	v_ldexp_f32 v4, v4, v5
	s_nop 0
	v_cndmask_b32_e32 v4, 0, v4, vcc
	v_cmp_nlt_f32_e32 vcc, s10, v3
	s_nop 1
	v_cndmask_b32_e32 v3, v200, v4, vcc
	v_sub_f32_e32 v0, v0, v3
	v_add_f32_e32 v28, v6, v0
	v_lshlrev_b32_e32 v0, 5, v2
	v_lshl_add_u64 v[34:35], s[24:25], 0, v[0:1]
	v_mov_b32_e32 v29, v28
	v_lshlrev_b64 v[112:113], 1, v[32:33]
	s_mov_b64 s[2:3], exec
	s_andn2_b64 exec, exec, s[38:39]
	v_lshlrev_b32_e32 v112, 1, v30
	v_mov_b32_e32 v113, 0
	v_add_u32_e32 v112, 0x800, v112
	s_mov_b64 exec, s[2:3]
	v_mov_b64_e32 v[114:115], s[4:5]
	s_nop 0
	v_mad_i64_i32 v[114:115], s[2:3], v10, s95, v[114:115]
	v_lshl_add_u64 v[116:117], v[114:115], 0, v[112:113]
	global_load_dwordx4 v[96:99], v[116:117], off nt
	global_load_dwordx4 v[100:103], v[116:117], off offset:16 nt
	global_load_dwordx4 v[104:107], v[116:117], off offset:1024 nt
	global_load_dwordx4 v[108:111], v[116:117], off offset:1040 nt
	s_waitcnt vmcnt(0)
	s_branch .Lmy_post_top

; DI float bflo(unsigned w) { return __uint_as_float(w << 16); }
; DI float bfhi(unsigned w) { return __uint_as_float(w & 0xffff0000u); }
; DI float shx(float v, int m) { const int lane = tid_() & 63; return __builtin_bit_cast(float, __builtin_amdgcn_ds_bpermute((lane ^ m) << 2, __builtin_bit_cast(int, v))); }
; DI float sigmoidf_(float x) { return 1.f / (1.f + __expf(-x)); }
; DI int bid_() { return (int)blockIdx.x; }
; DI void phase_post(const Params& p, int L) {
;     ...
;     for (int row = bid_() * 8 + wave; row < MTOK; row += gridDim.x * 8) {
;         const bf16_t* pr = P + (size_t)row * PE;
;         float o[16];
;         if (isa) { const u32x4 a = *(const u32x4*)(pr + 1024 + 16 * lane), bq = *(const u32x4*)(pr + 1024 + 16 * lane + 8);
;             const unsigned uw[8] = {a.x, a.y, a.z, a.w, bq.x, bq.y, bq.z, bq.w};
;             for (int q = 0; q < 8; ++q) { o[2 * q] = bflo(uw[q]); o[2 * q + 1] = bfhi(uw[q]); } }
;         else { const int l2 = lane - 32;
;             const u32x4 a = *(const u32x4*)(pr + 16 * l2), bq = *(const u32x4*)(pr + 16 * l2 + 8), c = *(const u32x4*)(pr + 512 + 16 * l2), d = *(const u32x4*)(pr + 512 + 16 * l2 + 8);
;             const unsigned u1[8] = {a.x, a.y, a.z, a.w, bq.x, bq.y, bq.z, bq.w}, u2[8] = {c.x, c.y, c.z, c.w, d.x, d.y, d.z, d.w};
;             for (int q = 0; q < 8; ++q) { o[2 * q] = bflo(u1[q]) - lam * bflo(u2[q]); o[2 * q + 1] = bfhi(u1[q]) - lam * bfhi(u2[q]); } }
;         float ss = 0.f; for (int e = 0; e < 16; ++e) ss += o[e] * o[e];
;         ss += shx(ss, 1); ss += shx(ss, 2); ss += shx(ss, 4);
;         const float rn = rsqrtf(ss * (1.f / 128.f) + EPS);
;         float g[16];
;         if (isa) { const u32x4 a = *(const u32x4*)(pr + 1536 + 16 * lane), bq = *(const u32x4*)(pr + 1536 + 16 * lane + 8);
;             const unsigned uw[8] = {a.x, a.y, a.z, a.w, bq.x, bq.y, bq.z, bq.w};
;             for (int q = 0; q < 8; ++q) { const float z0 = bflo(uw[q]), z1 = bfhi(uw[q]); g[2 * q] = z0 * sigmoidf_(z0); g[2 * q + 1] = z1 * sigmoidf_(z1); } }
;         else for (int e = 0; e < 16; ++e) g[e] = 1.f;
;         for (int e = 0; e < 16; ++e) o[e] = o[e] * rn * nw[e] * g[e];
.LBB0_617:
	s_or_b64 exec, exec, s[2:3]
	v_add_u32_e32 v118, s71, v10
	v_min_i32_e32 v118, 0x7fff, v118
	v_mov_b64_e32 v[114:115], s[4:5]
	s_nop 0
	v_mad_i64_i32 v[114:115], s[2:3], v118, s95, v[114:115]
	v_lshl_add_u64 v[116:117], v[114:115], 0, v[112:113]
	global_load_dwordx4 v[96:99], v[116:117], off nt
	global_load_dwordx4 v[100:103], v[116:117], off offset:16 nt
	global_load_dwordx4 v[104:107], v[116:117], off offset:1024 nt
	global_load_dwordx4 v[108:111], v[116:117], off offset:1040 nt
	v_mul_f32_e32 v0, v37, v37
	v_fmac_f32_e32 v0, v36, v36
	v_fmac_f32_e32 v0, v38, v38
	v_fmac_f32_e32 v0, v39, v39
	v_fmac_f32_e32 v0, v40, v40
	v_fmac_f32_e32 v0, v41, v41
	v_fmac_f32_e32 v0, v42, v42
	v_fmac_f32_e32 v0, v43, v43
	v_pk_mul_f32 v[52:53], v[44:45], v[44:45]
	v_pk_mul_f32 v[8:9], v[46:47], v[46:47]
	v_add_f32_e32 v0, v52, v0
	v_add_f32_e32 v0, v53, v0
	v_add_f32_e32 v0, v8, v0
	v_pk_mul_f32 v[6:7], v[48:49], v[48:49]
	v_add_f32_e32 v0, v9, v0
	v_add_f32_e32 v0, v6, v0
	v_pk_mul_f32 v[4:5], v[50:51], v[50:51]
	v_add_f32_e32 v0, v7, v0
	v_add_f32_e32 v0, v4, v0
	v_mov_b32_e32 v4, v194
	v_add_f32_e32 v0, v5, v0
	v_lshlrev_b32_e32 v4, 2, v4
	v_bitop3_b32 v4, v4, 4, v199 bitop3:0x6c
	ds_bpermute_b32 v4, v4, v0
	v_mov_b32_e32 v62, 1.0
	v_mov_b32_e32 v63, 1.0
	v_mov_b32_e32 v8, 1.0
	v_mov_b32_e32 v9, 1.0
	s_waitcnt lgkmcnt(0)
	v_add_f32_e32 v0, v0, v4
	v_mov_b32_e32 v4, v194
	v_mov_b32_e32 v54, 1.0
	v_lshlrev_b32_e32 v4, 2, v4
	v_bitop3_b32 v4, v4, 8, v199 bitop3:0x6c
	ds_bpermute_b32 v4, v4, v0
	v_mov_b32_e32 v55, 1.0
	v_mov_b32_e32 v6, 1.0
	v_mov_b32_e32 v7, 1.0
	v_mov_b32_e32 v56, 1.0
	s_waitcnt lgkmcnt(0)
	v_add_f32_e32 v11, v0, v4
	v_mov_b32_e32 v0, v194
	v_mov_b32_e32 v57, 1.0
	v_lshlrev_b32_e32 v0, 2, v0
	v_bitop3_b32 v0, v0, 16, v199 bitop3:0x6c
	ds_bpermute_b32 v31, v0, v11
	v_mov_b32_e32 v58, 1.0
	v_mov_b32_e32 v59, 1.0
	v_mov_b32_e32 v60, 1.0
	v_mov_b32_e32 v61, 1.0
	v_mov_b32_e32 v4, 1.0
	v_mov_b32_e32 v5, 1.0
	s_and_saveexec_b64 s[44:45], s[40:41]
	s_cbranch_execz .LBB0_612
	v_mov_b32_e32 v2, v88
	v_mov_b32_e32 v3, v89
	v_mov_b32_e32 v4, v90
	v_mov_b32_e32 v5, v91
	v_mov_b32_e32 v6, v92
	v_mov_b32_e32 v7, v93
	v_mov_b32_e32 v8, v94
	v_mov_b32_e32 v9, v95
	v_lshlrev_b32_e32 v53, 16, v6
	v_and_b32_e32 v52, 0xffff0000, v6
	v_mul_f32_e32 v0, 0xbfb8aa3b, v53
	v_exp_f32_e32 v55, v0
	v_mul_f32_e32 v0, 0xbfb8aa3b, v52
	v_exp_f32_e32 v54, v0
	s_nop 0
	v_pk_add_f32 v[54:55], v[54:55], 1.0 op_sel_hi:[1,0]
	s_nop 0
	v_div_scale_f32 v0, s[2:3], v55, v55, 1.0
	v_rcp_f32_e32 v6, v0
	s_nop 0
	v_fma_f32 v56, -v0, v6, 1.0
	v_fmac_f32_e32 v6, v56, v6
	v_div_scale_f32 v56, vcc, 1.0, v55, 1.0
	v_mul_f32_e32 v57, v56, v6
	v_fma_f32 v58, -v0, v57, v56
	v_fmac_f32_e32 v57, v58, v6
	v_fma_f32 v0, -v0, v57, v56
	v_div_fmas_f32 v0, v0, v6, v57
	v_div_fixup_f32 v55, v0, v55, 1.0
	v_div_scale_f32 v0, s[2:3], v54, v54, 1.0
	v_rcp_f32_e32 v6, v0
	s_nop 0
	v_fma_f32 v56, -v0, v6, 1.0
	v_fmac_f32_e32 v6, v56, v6
	v_div_scale_f32 v56, vcc, 1.0, v54, 1.0
	v_mul_f32_e32 v57, v56, v6
	v_fma_f32 v58, -v0, v57, v56
	v_fmac_f32_e32 v57, v58, v6
	v_fma_f32 v0, -v0, v57, v56
	v_div_fmas_f32 v0, v0, v6, v57
	v_and_b32_e32 v6, 0xffff0000, v7
	v_lshlrev_b32_e32 v7, 16, v7
	v_div_fixup_f32 v54, v0, v54, 1.0
	v_mul_f32_e32 v0, 0xbfb8aa3b, v7
	v_pk_mul_f32 v[52:53], v[54:55], v[52:53]
	v_exp_f32_e32 v55, v0
	v_mul_f32_e32 v0, 0xbfb8aa3b, v6
	v_exp_f32_e32 v54, v0
	s_nop 0
	v_pk_add_f32 v[54:55], v[54:55], 1.0 op_sel_hi:[1,0]
	s_nop 0
	v_div_scale_f32 v0, s[2:3], v55, v55, 1.0
	v_rcp_f32_e32 v56, v0
	s_nop 0
	v_fma_f32 v57, -v0, v56, 1.0
	v_fmac_f32_e32 v56, v57, v56
	v_div_scale_f32 v57, vcc, 1.0, v55, 1.0
	v_mul_f32_e32 v58, v57, v56
	v_fma_f32 v59, -v0, v58, v57
	v_fmac_f32_e32 v58, v59, v56
	v_fma_f32 v0, -v0, v58, v57
	v_div_fmas_f32 v0, v0, v56, v58
	v_div_fixup_f32 v55, v0, v55, 1.0
	v_div_scale_f32 v0, s[2:3], v54, v54, 1.0
	v_rcp_f32_e32 v56, v0
	s_nop 0
	v_fma_f32 v57, -v0, v56, 1.0
	v_fmac_f32_e32 v56, v57, v56
	v_div_scale_f32 v57, vcc, 1.0, v54, 1.0
	v_mul_f32_e32 v58, v57, v56
	v_fma_f32 v59, -v0, v58, v57
	v_fmac_f32_e32 v58, v59, v56
	v_fma_f32 v0, -v0, v58, v57
	v_div_fmas_f32 v0, v0, v56, v58
	v_div_fixup_f32 v54, v0, v54, 1.0
	v_pk_mul_f32 v[6:7], v[54:55], v[6:7]
	v_lshlrev_b32_e32 v55, 16, v8
	v_and_b32_e32 v54, 0xffff0000, v8
	v_mul_f32_e32 v0, 0xbfb8aa3b, v55
	v_exp_f32_e32 v57, v0
	v_mul_f32_e32 v0, 0xbfb8aa3b, v54
	v_exp_f32_e32 v56, v0
	s_nop 0
	v_pk_add_f32 v[56:57], v[56:57], 1.0 op_sel_hi:[1,0]
	s_nop 0
	v_div_scale_f32 v0, s[2:3], v57, v57, 1.0
	v_rcp_f32_e32 v8, v0
	s_nop 0
	v_fma_f32 v58, -v0, v8, 1.0
	v_fmac_f32_e32 v8, v58, v8
	v_div_scale_f32 v58, vcc, 1.0, v57, 1.0
	v_mul_f32_e32 v59, v58, v8
	v_fma_f32 v60, -v0, v59, v58
	v_fmac_f32_e32 v59, v60, v8
	v_fma_f32 v0, -v0, v59, v58
	v_div_fmas_f32 v0, v0, v8, v59
	v_div_fixup_f32 v57, v0, v57, 1.0
	v_div_scale_f32 v0, s[2:3], v56, v56, 1.0
	v_rcp_f32_e32 v8, v0
	s_nop 0
	v_fma_f32 v58, -v0, v8, 1.0
	v_fmac_f32_e32 v8, v58, v8
	v_div_scale_f32 v58, vcc, 1.0, v56, 1.0
	v_mul_f32_e32 v59, v58, v8
	v_fma_f32 v60, -v0, v59, v58
	v_fmac_f32_e32 v59, v60, v8
	v_fma_f32 v0, -v0, v59, v58
	v_div_fmas_f32 v0, v0, v8, v59
	v_and_b32_e32 v8, 0xffff0000, v9
	v_lshlrev_b32_e32 v9, 16, v9
; DI float bflo(unsigned w) { return __uint_as_float(w << 16); }
; DI float bfhi(unsigned w) { return __uint_as_float(w & 0xffff0000u); }
; DI float sigmoidf_(float x) { return 1.f / (1.f + __expf(-x)); }
; DI void phase_post(const Params& p, int L) {
;     ...
;         if (isa) { const u32x4 a = *(const u32x4*)(pr + 1536 + 16 * lane), bq = *(const u32x4*)(pr + 1536 + 16 * lane + 8);
;             const unsigned uw[8] = {a.x, a.y, a.z, a.w, bq.x, bq.y, bq.z, bq.w};
;             for (int q = 0; q < 8; ++q) { const float z0 = bflo(uw[q]), z1 = bfhi(uw[q]); g[2 * q] = z0 * sigmoidf_(z0); g[2 * q + 1] = z1 * sigmoidf_(z1); } }
;         else for (int e = 0; e < 16; ++e) g[e] = 1.f;
;         for (int e = 0; e < 16; ++e) o[e] = o[e] * rn * nw[e] * g[e];
	v_div_fixup_f32 v56, v0, v56, 1.0
	v_mul_f32_e32 v0, 0xbfb8aa3b, v9
	v_pk_mul_f32 v[54:55], v[56:57], v[54:55]
	v_exp_f32_e32 v57, v0
	v_mul_f32_e32 v0, 0xbfb8aa3b, v8
	v_exp_f32_e32 v56, v0
	s_nop 0
	v_pk_add_f32 v[56:57], v[56:57], 1.0 op_sel_hi:[1,0]
	s_nop 0
	v_div_scale_f32 v0, s[2:3], v57, v57, 1.0
	v_rcp_f32_e32 v58, v0
	s_nop 0
	v_fma_f32 v59, -v0, v58, 1.0
	v_fmac_f32_e32 v58, v59, v58
	v_div_scale_f32 v59, vcc, 1.0, v57, 1.0
	v_mul_f32_e32 v60, v59, v58
	v_fma_f32 v61, -v0, v60, v59
	v_fmac_f32_e32 v60, v61, v58
	v_fma_f32 v0, -v0, v60, v59
	v_div_fmas_f32 v0, v0, v58, v60
	v_div_fixup_f32 v57, v0, v57, 1.0
	v_div_scale_f32 v0, s[2:3], v56, v56, 1.0
	v_rcp_f32_e32 v58, v0
	s_nop 0
	v_fma_f32 v59, -v0, v58, 1.0
	v_fmac_f32_e32 v58, v59, v58
	v_div_scale_f32 v59, vcc, 1.0, v56, 1.0
	v_mul_f32_e32 v60, v59, v58
	v_fma_f32 v61, -v0, v60, v59
	v_fmac_f32_e32 v60, v61, v58
	v_fma_f32 v0, -v0, v60, v59
	v_div_fmas_f32 v0, v0, v58, v60
	v_div_fixup_f32 v56, v0, v56, 1.0
	v_pk_mul_f32 v[8:9], v[56:57], v[8:9]
	v_lshlrev_b32_e32 v56, 16, v2
	v_and_b32_e32 v57, 0xffff0000, v2
	v_mul_f32_e32 v0, 0xbfb8aa3b, v56
	v_exp_f32_e32 v58, v0
	v_mul_f32_e32 v0, 0xbfb8aa3b, v57
	v_exp_f32_e32 v59, v0
	s_nop 0
	v_pk_add_f32 v[58:59], v[58:59], 1.0 op_sel_hi:[1,0]
	s_nop 0
	v_div_scale_f32 v0, s[2:3], v59, v59, 1.0
	v_rcp_f32_e32 v2, v0
	s_nop 0
	v_fma_f32 v60, -v0, v2, 1.0
	v_fmac_f32_e32 v2, v60, v2
	v_div_scale_f32 v60, vcc, 1.0, v59, 1.0
	v_mul_f32_e32 v61, v60, v2
	v_fma_f32 v62, -v0, v61, v60
	v_fmac_f32_e32 v61, v62, v2
	v_fma_f32 v0, -v0, v61, v60
	v_div_fmas_f32 v0, v0, v2, v61
	v_div_fixup_f32 v59, v0, v59, 1.0
	v_div_scale_f32 v0, s[2:3], v58, v58, 1.0
	v_rcp_f32_e32 v2, v0
	s_nop 0
	v_fma_f32 v60, -v0, v2, 1.0
	v_fmac_f32_e32 v2, v60, v2
	v_div_scale_f32 v60, vcc, 1.0, v58, 1.0
	v_mul_f32_e32 v61, v60, v2
	v_fma_f32 v62, -v0, v61, v60
	v_fmac_f32_e32 v61, v62, v2
	v_fma_f32 v0, -v0, v61, v60
	v_div_fmas_f32 v0, v0, v2, v61
	v_lshlrev_b32_e32 v2, 16, v3
	v_div_fixup_f32 v58, v0, v58, 1.0
	v_and_b32_e32 v3, 0xffff0000, v3
	v_mul_f32_e32 v0, 0xbfb8aa3b, v2
	v_pk_mul_f32 v[56:57], v[58:59], v[56:57]
	v_exp_f32_e32 v58, v0
	v_mul_f32_e32 v0, 0xbfb8aa3b, v3
	v_exp_f32_e32 v59, v0
	s_nop 0
	v_pk_add_f32 v[58:59], v[58:59], 1.0 op_sel_hi:[1,0]
	s_nop 0
	v_div_scale_f32 v0, s[2:3], v59, v59, 1.0
	v_rcp_f32_e32 v60, v0
	s_nop 0
	v_fma_f32 v61, -v0, v60, 1.0
	v_fmac_f32_e32 v60, v61, v60
	v_div_scale_f32 v61, vcc, 1.0, v59, 1.0
	v_mul_f32_e32 v62, v61, v60
	v_fma_f32 v63, -v0, v62, v61
	v_fmac_f32_e32 v62, v63, v60
	v_fma_f32 v0, -v0, v62, v61
	v_div_fmas_f32 v0, v0, v60, v62
	v_div_fixup_f32 v59, v0, v59, 1.0
	v_div_scale_f32 v0, s[2:3], v58, v58, 1.0
	v_rcp_f32_e32 v60, v0
	s_nop 0
	v_fma_f32 v61, -v0, v60, 1.0
	v_fmac_f32_e32 v60, v61, v60
	v_div_scale_f32 v61, vcc, 1.0, v58, 1.0
	v_mul_f32_e32 v62, v61, v60
	v_fma_f32 v63, -v0, v62, v61
	v_fmac_f32_e32 v62, v63, v60
	v_fma_f32 v0, -v0, v62, v61
	v_div_fmas_f32 v0, v0, v60, v62
	v_div_fixup_f32 v58, v0, v58, 1.0
	v_pk_mul_f32 v[58:59], v[58:59], v[2:3]
	v_lshlrev_b32_e32 v2, 16, v4
	v_and_b32_e32 v3, 0xffff0000, v4
	v_mul_f32_e32 v0, 0xbfb8aa3b, v2
	v_exp_f32_e32 v60, v0
	v_mul_f32_e32 v0, 0xbfb8aa3b, v3
	v_exp_f32_e32 v61, v0
	s_nop 0
	v_pk_add_f32 v[60:61], v[60:61], 1.0 op_sel_hi:[1,0]
	s_nop 0
	v_div_scale_f32 v0, s[2:3], v61, v61, 1.0
	v_rcp_f32_e32 v4, v0
	s_nop 0
	v_fma_f32 v62, -v0, v4, 1.0
	v_fmac_f32_e32 v4, v62, v4
	v_div_scale_f32 v62, vcc, 1.0, v61, 1.0
	v_mul_f32_e32 v63, v62, v4
	v_fma_f32 v64, -v0, v63, v62
	v_fmac_f32_e32 v63, v64, v4
	v_fma_f32 v0, -v0, v63, v62
	v_div_fmas_f32 v0, v0, v4, v63
	v_div_fixup_f32 v61, v0, v61, 1.0
	v_div_scale_f32 v0, s[2:3], v60, v60, 1.0
	v_rcp_f32_e32 v4, v0
	s_nop 0
	v_fma_f32 v62, -v0, v4, 1.0
	v_fmac_f32_e32 v4, v62, v4
	v_div_scale_f32 v62, vcc, 1.0, v60, 1.0
	v_mul_f32_e32 v63, v62, v4
	v_fma_f32 v64, -v0, v63, v62
	v_fmac_f32_e32 v63, v64, v4
	v_fma_f32 v0, -v0, v63, v62
	v_div_fmas_f32 v0, v0, v4, v63
	v_div_fixup_f32 v60, v0, v60, 1.0
	v_pk_mul_f32 v[60:61], v[60:61], v[2:3]
	v_lshlrev_b32_e32 v2, 16, v5
	v_and_b32_e32 v3, 0xffff0000, v5
	v_mul_f32_e32 v0, 0xbfb8aa3b, v2
	v_exp_f32_e32 v4, v0
	v_mul_f32_e32 v0, 0xbfb8aa3b, v3
	v_exp_f32_e32 v5, v0
	s_nop 0
	v_pk_add_f32 v[4:5], v[4:5], 1.0 op_sel_hi:[1,0]
	s_nop 0
	v_div_scale_f32 v0, s[2:3], v5, v5, 1.0
	v_rcp_f32_e32 v62, v0
	s_nop 0
	v_fma_f32 v63, -v0, v62, 1.0
	v_fmac_f32_e32 v62, v63, v62
	v_div_scale_f32 v63, vcc, 1.0, v5, 1.0
	v_mul_f32_e32 v64, v63, v62
	v_fma_f32 v65, -v0, v64, v63
	v_fmac_f32_e32 v64, v65, v62
	v_fma_f32 v0, -v0, v64, v63
	v_div_fmas_f32 v0, v0, v62, v64
	v_div_fixup_f32 v5, v0, v5, 1.0
	v_div_scale_f32 v0, s[2:3], v4, v4, 1.0
	v_rcp_f32_e32 v62, v0
	s_nop 0
	v_fma_f32 v63, -v0, v62, 1.0
	v_fmac_f32_e32 v62, v63, v62
	v_div_scale_f32 v63, vcc, 1.0, v4, 1.0
	v_mul_f32_e32 v64, v63, v62
	v_fma_f32 v65, -v0, v64, v63
	v_fmac_f32_e32 v64, v65, v62
	v_fma_f32 v0, -v0, v64, v63
	v_div_fmas_f32 v0, v0, v62, v64
	v_div_fixup_f32 v4, v0, v4, 1.0
	v_pk_mul_f32 v[4:5], v[4:5], v[2:3]
	v_mov_b32_e32 v62, v9
	v_mov_b32_e32 v63, v8
	v_mov_b32_e32 v8, v55
	v_mov_b32_e32 v9, v54
	v_mov_b32_e32 v54, v7
	v_mov_b32_e32 v55, v6
	v_mov_b32_e32 v6, v53
	v_mov_b32_e32 v7, v52
	s_branch .LBB0_612
